# v23 plus counted lgkmcnt waits per MFMA in the MLA final-tile PV instead of full drains per group
# baseline (speedup 1.0000x reference)
.LBB0_583:
	v_add_f32_e32 v100, v84, v85
	v_fmac_f32_e32 v100, v222, v2
	ds_read_b64_tr_b16 v[84:85], v221 offset:0
	ds_read_b64_tr_b16 v[86:87], v221 offset:0x800
	ds_read_b64_tr_b16 v[88:89], v221 offset:0x1000
	ds_read_b64_tr_b16 v[90:91], v221 offset:0x1800
	ds_read_b64_tr_b16 v[92:93], v221 offset:0x2000
	ds_read_b64_tr_b16 v[94:95], v221 offset:0x2800
	ds_read_b64_tr_b16 v[96:97], v221 offset:0x3000
	ds_read_b64_tr_b16 v[98:99], v221 offset:0x3800
	s_waitcnt lgkmcnt(6)
	s_nop 0
	v_mfma_f32_32x32x16_bf16 v[4:19], v[68:71], v[84:87], v[4:19]
	ds_read_b64_tr_b16 v[84:85], v221 offset:0x200
	ds_read_b64_tr_b16 v[86:87], v221 offset:0xa00
	s_waitcnt lgkmcnt(6)
	v_mfma_f32_32x32x16_bf16 v[4:19], v[72:75], v[88:91], v[4:19]
	ds_read_b64_tr_b16 v[88:89], v221 offset:0x1200
	ds_read_b64_tr_b16 v[90:91], v221 offset:0x1a00
	s_waitcnt lgkmcnt(6)
	v_mfma_f32_32x32x16_bf16 v[4:19], v[76:79], v[92:95], v[4:19]
	ds_read_b64_tr_b16 v[92:93], v221 offset:0x2200
	ds_read_b64_tr_b16 v[94:95], v221 offset:0x2a00
	s_waitcnt lgkmcnt(6)
	v_mfma_f32_32x32x16_bf16 v[4:19], v[80:83], v[96:99], v[4:19]
	ds_read_b64_tr_b16 v[96:97], v221 offset:0x3200
	ds_read_b64_tr_b16 v[98:99], v221 offset:0x3a00
	s_waitcnt lgkmcnt(6)
	v_mfma_f32_32x32x16_bf16 v[52:67], v[68:71], v[84:87], v[52:67]
	ds_read_b64_tr_b16 v[84:85], v221 offset:0x400
	ds_read_b64_tr_b16 v[86:87], v221 offset:0xc00
	s_waitcnt lgkmcnt(6)
	v_mfma_f32_32x32x16_bf16 v[52:67], v[72:75], v[88:91], v[52:67]
	ds_read_b64_tr_b16 v[88:89], v221 offset:0x1400
	ds_read_b64_tr_b16 v[90:91], v221 offset:0x1c00
	s_waitcnt lgkmcnt(6)
	v_mfma_f32_32x32x16_bf16 v[52:67], v[76:79], v[92:95], v[52:67]
	ds_read_b64_tr_b16 v[92:93], v221 offset:0x2400
	ds_read_b64_tr_b16 v[94:95], v221 offset:0x2c00
	s_waitcnt lgkmcnt(6)
	v_mfma_f32_32x32x16_bf16 v[52:67], v[80:83], v[96:99], v[52:67]
	ds_read_b64_tr_b16 v[96:97], v221 offset:0x3400
	ds_read_b64_tr_b16 v[98:99], v221 offset:0x3c00
	s_waitcnt lgkmcnt(6)
	v_mfma_f32_32x32x16_bf16 v[20:35], v[68:71], v[84:87], v[20:35]
	ds_read_b64_tr_b16 v[84:85], v221 offset:0x600
	ds_read_b64_tr_b16 v[86:87], v221 offset:0xe00
	s_waitcnt lgkmcnt(6)
	v_mfma_f32_32x32x16_bf16 v[20:35], v[72:75], v[88:91], v[20:35]
	ds_read_b64_tr_b16 v[88:89], v221 offset:0x1600
	ds_read_b64_tr_b16 v[90:91], v221 offset:0x1e00
	s_waitcnt lgkmcnt(6)
	v_mfma_f32_32x32x16_bf16 v[20:35], v[76:79], v[92:95], v[20:35]
	ds_read_b64_tr_b16 v[92:93], v221 offset:0x2600
	ds_read_b64_tr_b16 v[94:95], v221 offset:0x2e00
	s_waitcnt lgkmcnt(6)
	v_mfma_f32_32x32x16_bf16 v[20:35], v[80:83], v[96:99], v[20:35]
	ds_read_b64_tr_b16 v[96:97], v221 offset:0x3600
	ds_read_b64_tr_b16 v[98:99], v221 offset:0x3e00
	s_waitcnt lgkmcnt(6)
	v_mfma_f32_32x32x16_bf16 v[36:51], v[68:71], v[84:87], v[36:51]
	v_mov_b32_e32 v222, v100
	s_waitcnt lgkmcnt(4)
	v_mfma_f32_32x32x16_bf16 v[36:51], v[72:75], v[88:91], v[36:51]
	s_waitcnt lgkmcnt(2)
	v_mfma_f32_32x32x16_bf16 v[36:51], v[76:79], v[92:95], v[36:51]
	s_waitcnt lgkmcnt(0)
	v_mfma_f32_32x32x16_bf16 v[36:51], v[80:83], v[96:99], v[36:51]
